# attention tail: hand-written next-chunk weight conversion (16-byte loads, gain loads issued together)
# speedup vs baseline: 1.0039x; 1.0039x over previous
.Lcva_entry:
	v_readlane_b32 s36, v253, 52
	v_readlane_b32 s42, v254, 46
	v_readlane_b32 s43, v254, 47
	v_mbcnt_lo_u32_b32 v0, -1, 0
	v_mbcnt_hi_u32_b32 v0, -1, v0
	v_lshrrev_b32_e32 v1, 3, v0
	v_and_b32_e32 v2, 7, v0
	v_mul_u32_u24_e32 v8, 0x84, v1
	v_lshl_add_u32 v8, v2, 4, v8
	v_add_u32_e32 v8, s36, v8
	v_mul_u32_u24_e32 v9, 0x420, v2
	v_lshl_add_u32 v9, v1, 2, v9
	v_add_u32_e32 v9, s36, v9
	v_lshlrev_b32_e32 v10, 11, v1
	v_lshl_add_u32 v10, v2, 4, v10
	v_mov_b32_e32 v11, 0
	v_mov_b32_e32 v13, 0
.Lcva_loop:
	s_lshr_b32 s12, s35, s22
	s_lshl_b32 s13, 1, s22
	s_add_i32 s13, s13, -1
	s_and_b32 s13, s35, s13
	s_add_i32 s14, s22, -4
	s_lshr_b32 s15, s13, s14
	s_add_i32 s18, s25, -1
	s_and_b32 s18, s13, s18
	s_mov_b64 s[20:21], s[6:7]
	s_mov_b32 s19, 0x8000
	s_mov_b64 s[36:37], s[48:49]
	s_mov_b32 s38, 0x3e0293ee
	s_mov_b32 s14, 0
	s_cmp_eq_u32 s12, 0
	s_cbranch_scc1 .Lcva_sel
	s_mov_b32 s38, 1.0
	s_cmp_eq_u32 s12, 1
	s_cbranch_scc0 .Lcva_s2
	s_mov_b64 s[20:21], s[0:1]
	s_mov_b32 s19, 0xc000
	s_mov_b64 s[36:37], s[44:45]
	s_mov_b32 s14, s24
	s_branch .Lcva_sel
.Lcva_s2:
	s_cmp_eq_u32 s12, s27
	s_cbranch_scc0 .Lcva_s3
	s_add_u32 s20, s0, 0x6000
	s_addc_u32 s21, s1, 0
	s_mov_b32 s19, 0xc000
	s_mov_b64 s[36:37], s[44:45]
	s_mul_i32 s14, s27, s24
	s_branch .Lcva_sel
.Lcva_s3:
	s_add_u32 s20, s10, 0x6000
	s_addc_u32 s21, s11, 0
	s_lshl_b32 s14, s24, 1
.Lcva_sel:
	s_lshl_b32 s12, s15, 6
	s_mul_i32 s12, s12, s19
	s_lshl_b32 s13, s18, 7
	s_add_u32 s12, s12, s13
	s_add_u32 s98, s20, s12
	s_addc_u32 s99, s21, 0
	s_lshl_b32 s100, s19, 3
	s_mov_b32 s101, 0
	v_mul_u32_u24_e32 v3, s19, v1
	v_lshl_add_u32 v12, v2, 4, v3
	v_lshl_add_u64 v[4:5], s[98:99], 0, v[12:13]
	global_load_dwordx4 v[16:19], v[4:5], off
	v_lshl_add_u64 v[4:5], s[100:101], 0, v[4:5]
	global_load_dwordx4 v[20:23], v[4:5], off
	v_lshl_add_u64 v[4:5], s[100:101], 0, v[4:5]
	global_load_dwordx4 v[24:27], v[4:5], off
	v_lshl_add_u64 v[4:5], s[100:101], 0, v[4:5]
	global_load_dwordx4 v[28:31], v[4:5], off
	v_lshl_add_u64 v[4:5], s[100:101], 0, v[4:5]
	global_load_dwordx4 v[32:35], v[4:5], off
	v_lshl_add_u64 v[4:5], s[100:101], 0, v[4:5]
	global_load_dwordx4 v[36:39], v[4:5], off
	v_lshl_add_u64 v[4:5], s[100:101], 0, v[4:5]
	global_load_dwordx4 v[40:43], v[4:5], off
	v_lshl_add_u64 v[4:5], s[100:101], 0, v[4:5]
	global_load_dwordx4 v[44:47], v[4:5], off
	s_lshl_b32 s12, s15, 8
	v_lshl_add_u32 v12, v1, 2, s12
	v_lshl_add_u64 v[6:7], s[36:37], 0, v[12:13]
	global_load_dword v48, v[6:7], off
	global_load_dword v49, v[6:7], off offset:32
	global_load_dword v50, v[6:7], off offset:64
	global_load_dword v51, v[6:7], off offset:96
	global_load_dword v52, v[6:7], off offset:128
	global_load_dword v53, v[6:7], off offset:160
	global_load_dword v54, v[6:7], off offset:192
	global_load_dword v55, v[6:7], off offset:224
	s_lshl_b32 s13, s18, 5
	s_add_i32 s13, s13, s14
	s_lshl_b32 s13, s13, 11
	s_lshl_b32 s12, s15, 7
	s_add_u32 s13, s13, s12
	s_add_u32 s98, s42, s13
	s_addc_u32 s99, s43, 0
	v_lshl_add_u64 v[14:15], s[98:99], 0, v[10:11]
	s_movk_i32 s100, 0x4000
	s_waitcnt vmcnt(0)
	v_mul_f32_e32 v48, s38, v48
	v_mul_f32_e32 v49, s38, v49
	v_mul_f32_e32 v50, s38, v50
	v_mul_f32_e32 v51, s38, v51
	v_mul_f32_e32 v52, s38, v52
	v_mul_f32_e32 v53, s38, v53
	v_mul_f32_e32 v54, s38, v54
	v_mul_f32_e32 v55, s38, v55
	v_mul_f32_e32 v16, v16, v48
	v_mul_f32_e32 v17, v17, v48
	v_mul_f32_e32 v18, v18, v48
	v_mul_f32_e32 v19, v19, v48
	v_mul_f32_e32 v20, v20, v49
	v_mul_f32_e32 v21, v21, v49
	v_mul_f32_e32 v22, v22, v49
	v_mul_f32_e32 v23, v23, v49
	v_mul_f32_e32 v24, v24, v50
	v_mul_f32_e32 v25, v25, v50
	v_mul_f32_e32 v26, v26, v50
	v_mul_f32_e32 v27, v27, v50
	v_mul_f32_e32 v28, v28, v51
	v_mul_f32_e32 v29, v29, v51
	v_mul_f32_e32 v30, v30, v51
	v_mul_f32_e32 v31, v31, v51
	v_mul_f32_e32 v32, v32, v52
	v_mul_f32_e32 v33, v33, v52
	v_mul_f32_e32 v34, v34, v52
	v_mul_f32_e32 v35, v35, v52
	v_mul_f32_e32 v36, v36, v53
	v_mul_f32_e32 v37, v37, v53
	v_mul_f32_e32 v38, v38, v53
	v_mul_f32_e32 v39, v39, v53
	v_mul_f32_e32 v40, v40, v54
	v_mul_f32_e32 v41, v41, v54
	v_mul_f32_e32 v42, v42, v54
	v_mul_f32_e32 v43, v43, v54
	v_mul_f32_e32 v44, v44, v55
	v_mul_f32_e32 v45, v45, v55
	v_mul_f32_e32 v46, v46, v55
	v_mul_f32_e32 v47, v47, v55
	ds_write_b32 v8, v16 offset:0
	ds_write_b32 v8, v17 offset:4
	ds_write_b32 v8, v18 offset:8
	ds_write_b32 v8, v19 offset:12
	ds_write_b32 v8, v20 offset:1056
	ds_write_b32 v8, v21 offset:1060
	ds_write_b32 v8, v22 offset:1064
	ds_write_b32 v8, v23 offset:1068
	ds_write_b32 v8, v24 offset:2112
	ds_write_b32 v8, v25 offset:2116
	ds_write_b32 v8, v26 offset:2120
	ds_write_b32 v8, v27 offset:2124
	ds_write_b32 v8, v28 offset:3168
	ds_write_b32 v8, v29 offset:3172
	ds_write_b32 v8, v30 offset:3176
	ds_write_b32 v8, v31 offset:3180
	ds_write_b32 v8, v32 offset:4224
	ds_write_b32 v8, v33 offset:4228
	ds_write_b32 v8, v34 offset:4232
	ds_write_b32 v8, v35 offset:4236
	ds_write_b32 v8, v36 offset:5280
	ds_write_b32 v8, v37 offset:5284
	ds_write_b32 v8, v38 offset:5288
	ds_write_b32 v8, v39 offset:5292
	ds_write_b32 v8, v40 offset:6336
	ds_write_b32 v8, v41 offset:6340
	ds_write_b32 v8, v42 offset:6344
	ds_write_b32 v8, v43 offset:6348
	ds_write_b32 v8, v44 offset:7392
	ds_write_b32 v8, v45 offset:7396
	ds_write_b32 v8, v46 offset:7400
	ds_write_b32 v8, v47 offset:7404
	s_waitcnt lgkmcnt(0)
	ds_read_b32 v16, v9 offset:0
	ds_read_b32 v17, v9 offset:132
	ds_read_b32 v18, v9 offset:264
	ds_read_b32 v19, v9 offset:396
	ds_read_b32 v20, v9 offset:528
	ds_read_b32 v21, v9 offset:660
	ds_read_b32 v22, v9 offset:792
	ds_read_b32 v23, v9 offset:924
	s_waitcnt lgkmcnt(0)
	v_cvt_pk_bf16_f32 v24, v16, v17
	v_cvt_pk_bf16_f32 v25, v18, v19
	v_cvt_pk_bf16_f32 v26, v20, v21
	v_cvt_pk_bf16_f32 v27, v22, v23
	global_store_dwordx4 v[14:15], v[24:27], off sc1
	v_lshl_add_u64 v[14:15], s[100:101], 0, v[14:15]
	ds_read_b32 v16, v9 offset:32
	ds_read_b32 v17, v9 offset:164
	ds_read_b32 v18, v9 offset:296
	ds_read_b32 v19, v9 offset:428
	ds_read_b32 v20, v9 offset:560
	ds_read_b32 v21, v9 offset:692
	ds_read_b32 v22, v9 offset:824
	ds_read_b32 v23, v9 offset:956
	s_waitcnt lgkmcnt(0)
	v_cvt_pk_bf16_f32 v28, v16, v17
	v_cvt_pk_bf16_f32 v29, v18, v19
	v_cvt_pk_bf16_f32 v30, v20, v21
	v_cvt_pk_bf16_f32 v31, v22, v23
	global_store_dwordx4 v[14:15], v[28:31], off sc1
	v_lshl_add_u64 v[14:15], s[100:101], 0, v[14:15]
	ds_read_b32 v16, v9 offset:64
	ds_read_b32 v17, v9 offset:196
	ds_read_b32 v18, v9 offset:328
	ds_read_b32 v19, v9 offset:460
	ds_read_b32 v20, v9 offset:592
	ds_read_b32 v21, v9 offset:724
	ds_read_b32 v22, v9 offset:856
	ds_read_b32 v23, v9 offset:988
	s_waitcnt lgkmcnt(0)
	v_cvt_pk_bf16_f32 v32, v16, v17
	v_cvt_pk_bf16_f32 v33, v18, v19
	v_cvt_pk_bf16_f32 v34, v20, v21
	v_cvt_pk_bf16_f32 v35, v22, v23
	global_store_dwordx4 v[14:15], v[32:35], off sc1
	v_lshl_add_u64 v[14:15], s[100:101], 0, v[14:15]
	ds_read_b32 v16, v9 offset:96
	ds_read_b32 v17, v9 offset:228
	ds_read_b32 v18, v9 offset:360
	ds_read_b32 v19, v9 offset:492
	ds_read_b32 v20, v9 offset:624
	ds_read_b32 v21, v9 offset:756
	ds_read_b32 v22, v9 offset:888
	ds_read_b32 v23, v9 offset:1020
	s_waitcnt lgkmcnt(0)
	v_cvt_pk_bf16_f32 v36, v16, v17
	v_cvt_pk_bf16_f32 v37, v18, v19
	v_cvt_pk_bf16_f32 v38, v20, v21
	v_cvt_pk_bf16_f32 v39, v22, v23
	global_store_dwordx4 v[14:15], v[36:39], off sc1
	s_add_i32 s35, s35, s39
	s_cmp_lt_i32 s35, s23
	s_cbranch_scc1 .Lcva_loop
	s_branch .LBB0_1426

amdhsa.kernels:
  - .agpr_count:     0
    .args:
      - .offset:         0
        .size:           128
        .value_kind:     by_value
      - .offset:         128
        .size:           4
        .value_kind:     hidden_block_count_x
      - .offset:         132
        .size:           4
        .value_kind:     hidden_block_count_y
      - .offset:         136
        .size:           4
        .value_kind:     hidden_block_count_z
      - .offset:         140
        .size:           2
        .value_kind:     hidden_group_size_x
      - .offset:         142
        .size:           2
        .value_kind:     hidden_group_size_y
      - .offset:         144
        .size:           2
        .value_kind:     hidden_group_size_z
      - .offset:         146
        .size:           2
        .value_kind:     hidden_remainder_x
      - .offset:         148
        .size:           2
        .value_kind:     hidden_remainder_y
      - .offset:         150
        .size:           2
        .value_kind:     hidden_remainder_z
      - .offset:         168
        .size:           8
        .value_kind:     hidden_global_offset_x
      - .offset:         176
        .size:           8
        .value_kind:     hidden_global_offset_y
      - .offset:         184
        .size:           8
        .value_kind:     hidden_global_offset_z
      - .offset:         192
        .size:           2
        .value_kind:     hidden_grid_dims
      - .offset:         216
        .size:           8
        .value_kind:     hidden_multigrid_sync_arg
      - .offset:         248
        .size:           4
        .value_kind:     hidden_dynamic_lds_size
    .group_segment_fixed_size: 0
    .kernarg_segment_align: 8
    .kernarg_segment_size: 384
    .language:       OpenCL C
    .language_version:
      - 2
      - 0
    .max_flat_workgroup_size: 512
    .name:           _Z8yoco_fwd6Params
    .private_segment_fixed_size: 0
    .sgpr_count:     108
    .sgpr_spill_count: 130
    .symbol:         _Z8yoco_fwd6Params.kd
    .uniform_work_group_size: 1
    .uses_dynamic_stack: false
    .vgpr_count:     256
    .vgpr_spill_count: 0
    .wavefront_size: 64
